# same hand-written 3-slot dual-tile k-loop now also in the FFN down projection and the gate projection of phase 4
# speedup vs baseline: 1.0328x; 1.0165x over previous
.LBB0_767:
	s_mul_hi_i32 s8, s11, 0xf6603d99
	s_add_i32 s8, s8, s11
	s_lshr_b32 s9, s8, 31
	s_ashr_i32 s8, s8, 7
	s_add_i32 s12, s8, s9
	s_mul_i32 s8, s12, 0xffffff7b
	s_add_i32 s8, s8, s11
	s_lshl_b32 s13, s12, 7
	s_lshl_b32 s33, s8, 7
	s_add_i32 s8, s13, 0x1980
	s_ashr_i32 s9, s8, 31
	s_lshl_b64 s[8:9], s[8:9], 11
	s_add_u32 s16, s30, s8
	s_addc_u32 s17, s31, s9
	s_add_i32 s20, s13, 0x1d80
	v_add_u32_e32 v0, s33, v175
	s_ashr_i32 s21, s20, 31
	v_med3_i32 v0, v0, 0, v188
	v_add_u32_e32 v1, s33, v176
	v_readfirstlane_b32 s33, v177
	s_lshl_b64 s[20:21], s[20:21], 11
	v_lshl_or_b32 v0, v0, 11, v189
	s_mov_b32 m0, s33
	v_readfirstlane_b32 s33, v191
	s_add_u32 s24, s30, s20
	global_load_lds_dwordx4 v0, s[50:51]
	s_mov_b32 m0, s33
	v_readfirstlane_b32 s33, v192
	s_addc_u32 s25, s31, s21
	v_med3_i32 v1, v1, 0, v188
	global_load_lds_dwordx4 v190, s[16:17]
	s_mov_b32 m0, s33
	v_readfirstlane_b32 s33, v193
	global_load_lds_dwordx4 v190, s[24:25]
	v_lshl_or_b32 v0, v1, 11, v189
	s_mov_b32 m0, s33
	v_readfirstlane_b32 s33, v195
	global_load_lds_dwordx4 v0, s[50:51]
	s_mov_b32 m0, s33
	s_mulk_i32 s12, 0x4280
	global_load_lds_dwordx4 v194, s[16:17]
	v_readfirstlane_b32 s16, v196
	s_mov_b32 m0, s16
	v_subrev_u32_e32 v0, s12, v186
	global_load_lds_dwordx4 v194, s[24:25]
	v_med3_i32 v0, v0, 0, v188
	v_lshl_or_b32 v130, v0, 11, v189
	v_subrev_u32_e32 v0, s12, v187
	v_med3_i32 v0, v0, 0, v188
	v_lshl_add_u64 v[136:137], s[6:7], 0, v[130:131]
	v_lshl_or_b32 v130, v0, 11, v189
	v_lshl_add_u64 v[138:139], s[6:7], 0, v[130:131]
	v_lshl_add_u64 v[140:141], v[132:133], 0, s[8:9]
	v_lshl_add_u64 v[142:143], v[134:135], 0, s[8:9]
	v_lshl_add_u64 v[144:145], v[132:133], 0, s[20:21]
	v_lshl_add_u64 v[146:147], v[134:135], 0, s[20:21]
	v_add_u32_e32 v254, v179, v180
	v_readfirstlane_b32 s24, v177
	s_add_i32 s21, s24, 0x6000
	s_mov_b32 m0, s21
	s_nop 0
	global_load_lds_dwordx4 v[136:137], off
	v_lshl_add_u64 v[136:137], v[136:137], 0, 64
	s_add_i32 m0, s21, 0x2000
	s_nop 0
	global_load_lds_dwordx4 v[140:141], off
	v_lshl_add_u64 v[140:141], v[140:141], 0, 64
	s_add_i32 m0, s21, 0x4000
	s_nop 0
	global_load_lds_dwordx4 v[144:145], off
	v_lshl_add_u64 v[144:145], v[144:145], 0, 64
	s_add_i32 m0, s21, 0x400
	s_nop 0
	global_load_lds_dwordx4 v[138:139], off
	v_lshl_add_u64 v[138:139], v[138:139], 0, 64
	s_add_i32 m0, s21, 0x2400
	s_nop 0
	global_load_lds_dwordx4 v[142:143], off
	v_lshl_add_u64 v[142:143], v[142:143], 0, 64
	s_add_i32 m0, s21, 0x4400
	s_nop 0
	global_load_lds_dwordx4 v[146:147], off
	v_lshl_add_u64 v[146:147], v[146:147], 0, 64
	v_mov_b32_e32 v0, 0
	v_mov_b32_e32 v1, 0
	v_mov_b32_e32 v2, 0
	v_mov_b32_e32 v3, 0
	v_mov_b32_e32 v4, 0
	v_mov_b32_e32 v5, 0
	v_mov_b32_e32 v6, 0
	v_mov_b32_e32 v7, 0
	v_mov_b32_e32 v8, 0
	v_mov_b32_e32 v9, 0
	v_mov_b32_e32 v10, 0
	v_mov_b32_e32 v11, 0
	v_mov_b32_e32 v12, 0
	v_mov_b32_e32 v13, 0
	v_mov_b32_e32 v14, 0
	v_mov_b32_e32 v15, 0
	v_mov_b32_e32 v16, 0
	v_mov_b32_e32 v17, 0
	v_mov_b32_e32 v18, 0
	v_mov_b32_e32 v19, 0
	v_mov_b32_e32 v20, 0
	v_mov_b32_e32 v21, 0
	v_mov_b32_e32 v22, 0
	v_mov_b32_e32 v23, 0
	v_mov_b32_e32 v24, 0
	v_mov_b32_e32 v25, 0
	v_mov_b32_e32 v26, 0
	v_mov_b32_e32 v27, 0
	v_mov_b32_e32 v28, 0
	v_mov_b32_e32 v29, 0
	v_mov_b32_e32 v30, 0
	v_mov_b32_e32 v31, 0
	v_mov_b32_e32 v32, 0
	v_mov_b32_e32 v33, 0
	v_mov_b32_e32 v34, 0
	v_mov_b32_e32 v35, 0
	v_mov_b32_e32 v36, 0
	v_mov_b32_e32 v37, 0
	v_mov_b32_e32 v38, 0
	v_mov_b32_e32 v39, 0
	v_mov_b32_e32 v40, 0
	v_mov_b32_e32 v41, 0
	v_mov_b32_e32 v42, 0
	v_mov_b32_e32 v43, 0
	v_mov_b32_e32 v44, 0
	v_mov_b32_e32 v45, 0
	v_mov_b32_e32 v46, 0
	v_mov_b32_e32 v47, 0
	v_mov_b32_e32 v48, 0
	v_mov_b32_e32 v49, 0
	v_mov_b32_e32 v50, 0
	v_mov_b32_e32 v51, 0
	v_mov_b32_e32 v52, 0
	v_mov_b32_e32 v53, 0
	v_mov_b32_e32 v54, 0
	v_mov_b32_e32 v55, 0
	v_mov_b32_e32 v56, 0
	v_mov_b32_e32 v57, 0
	v_mov_b32_e32 v58, 0
	v_mov_b32_e32 v59, 0
	v_mov_b32_e32 v60, 0
	v_mov_b32_e32 v61, 0
	v_mov_b32_e32 v62, 0
	v_mov_b32_e32 v63, 0
	v_mov_b32_e32 v64, 0
	v_mov_b32_e32 v65, 0
	v_mov_b32_e32 v66, 0
	v_mov_b32_e32 v67, 0
	v_mov_b32_e32 v68, 0
	v_mov_b32_e32 v69, 0
	v_mov_b32_e32 v70, 0
	v_mov_b32_e32 v71, 0
	v_mov_b32_e32 v72, 0
	v_mov_b32_e32 v73, 0
	v_mov_b32_e32 v74, 0
	v_mov_b32_e32 v75, 0
	v_mov_b32_e32 v76, 0
	v_mov_b32_e32 v77, 0
	v_mov_b32_e32 v78, 0
	v_mov_b32_e32 v79, 0
	v_mov_b32_e32 v80, 0
	v_mov_b32_e32 v81, 0
	v_mov_b32_e32 v82, 0
	v_mov_b32_e32 v83, 0
	v_mov_b32_e32 v84, 0
	v_mov_b32_e32 v85, 0
	v_mov_b32_e32 v86, 0
	v_mov_b32_e32 v87, 0
	v_mov_b32_e32 v88, 0
	v_mov_b32_e32 v89, 0
	v_mov_b32_e32 v90, 0
	v_mov_b32_e32 v91, 0
	v_mov_b32_e32 v92, 0
	v_mov_b32_e32 v93, 0
	v_mov_b32_e32 v94, 0
	v_mov_b32_e32 v95, 0
	v_mov_b32_e32 v96, 0
	v_mov_b32_e32 v97, 0
	v_mov_b32_e32 v98, 0
	v_mov_b32_e32 v99, 0
	v_mov_b32_e32 v100, 0
	v_mov_b32_e32 v101, 0
	v_mov_b32_e32 v102, 0
	v_mov_b32_e32 v103, 0
	v_mov_b32_e32 v104, 0
	v_mov_b32_e32 v105, 0
	v_mov_b32_e32 v106, 0
	v_mov_b32_e32 v107, 0
	v_mov_b32_e32 v108, 0
	v_mov_b32_e32 v109, 0
	v_mov_b32_e32 v110, 0
	v_mov_b32_e32 v111, 0
	v_mov_b32_e32 v112, 0
	v_mov_b32_e32 v113, 0
	v_mov_b32_e32 v114, 0
	v_mov_b32_e32 v115, 0
	v_mov_b32_e32 v116, 0
	v_mov_b32_e32 v117, 0
	v_mov_b32_e32 v118, 0
	v_mov_b32_e32 v119, 0
	v_mov_b32_e32 v120, 0
	v_mov_b32_e32 v121, 0
	v_mov_b32_e32 v122, 0
	v_mov_b32_e32 v123, 0
	v_mov_b32_e32 v124, 0
	v_mov_b32_e32 v125, 0
	v_mov_b32_e32 v126, 0
	v_mov_b32_e32 v127, 0
	s_mov_b32 s16, 0
	s_mov_b32 s17, 0
	s_mov_b32 s20, 0xc000
.Lp5a_loop:
	s_waitcnt vmcnt(6)
	s_barrier
	v_add_u32_e32 v252, s17, v254
	v_add_u32_e32 v253, s17, v181
	s_add_i32 s21, s24, s20
	ds_read_b128 v[198:201], v252
	ds_read_b128 v[202:205], v253 offset:8192
	ds_read_b128 v[214:217], v253 offset:16384
	ds_read_b128 v[210:213], v253 offset:9216
	ds_read_b128 v[218:221], v253 offset:17408
	ds_read_b128 v[222:225], v253 offset:10240
	ds_read_b128 v[230:233], v253 offset:18432
	ds_read_b128 v[226:229], v253 offset:11264
	ds_read_b128 v[234:237], v253 offset:19456
	ds_read_b128 v[206:209], v252 offset:1024
	s_mov_b32 m0, s21
	s_nop 0
	global_load_lds_dwordx4 v[136:137], off
	v_lshl_add_u64 v[136:137], v[136:137], 0, 64
	s_add_i32 m0, s21, 0x2000
	s_nop 0
	global_load_lds_dwordx4 v[140:141], off
	v_lshl_add_u64 v[140:141], v[140:141], 0, 64
	s_waitcnt lgkmcnt(8)
	v_mfma_f32_16x16x32_f16 v[108:111], v[198:201], v[202:205], v[108:111]
	s_waitcnt lgkmcnt(7)
	v_mfma_f32_16x16x32_f16 v[124:127], v[198:201], v[214:217], v[124:127]
	s_waitcnt lgkmcnt(6)
	v_mfma_f32_16x16x32_f16 v[104:107], v[198:201], v[210:213], v[104:107]
	s_add_i32 m0, s21, 0x4000
	s_waitcnt lgkmcnt(5)
	v_mfma_f32_16x16x32_f16 v[120:123], v[198:201], v[218:221], v[120:123]
	global_load_lds_dwordx4 v[144:145], off
	v_lshl_add_u64 v[144:145], v[144:145], 0, 64
	s_waitcnt lgkmcnt(4)
	v_mfma_f32_16x16x32_f16 v[96:99], v[198:201], v[222:225], v[96:99]
	s_waitcnt lgkmcnt(3)
	v_mfma_f32_16x16x32_f16 v[116:119], v[198:201], v[230:233], v[116:119]
	s_waitcnt lgkmcnt(2)
	v_mfma_f32_16x16x32_f16 v[80:83], v[198:201], v[226:229], v[80:83]
	s_waitcnt lgkmcnt(1)
	v_mfma_f32_16x16x32_f16 v[112:115], v[198:201], v[234:237], v[112:115]
	ds_read_b128 v[240:243], v252 offset:2048
	ds_read_b128 v[244:247], v252 offset:3072
	s_waitcnt lgkmcnt(2)
	v_mfma_f32_16x16x32_f16 v[68:71], v[206:209], v[202:205], v[68:71]
	v_mfma_f32_16x16x32_f16 v[100:103], v[206:209], v[214:217], v[100:103]
	v_mfma_f32_16x16x32_f16 v[48:51], v[206:209], v[210:213], v[48:51]
	s_add_i32 m0, s21, 0x400
	v_mfma_f32_16x16x32_f16 v[92:95], v[206:209], v[218:221], v[92:95]
	global_load_lds_dwordx4 v[138:139], off
	v_lshl_add_u64 v[138:139], v[138:139], 0, 64
	v_mfma_f32_16x16x32_f16 v[40:43], v[206:209], v[222:225], v[40:43]
	v_mfma_f32_16x16x32_f16 v[88:91], v[206:209], v[230:233], v[88:91]
	v_mfma_f32_16x16x32_f16 v[32:35], v[206:209], v[226:229], v[32:35]
	v_mfma_f32_16x16x32_f16 v[84:87], v[206:209], v[234:237], v[84:87]
	s_waitcnt lgkmcnt(1)
	v_mfma_f32_16x16x32_f16 v[24:27], v[240:243], v[202:205], v[24:27]
	v_mfma_f32_16x16x32_f16 v[72:75], v[240:243], v[214:217], v[72:75]
	v_mfma_f32_16x16x32_f16 v[16:19], v[240:243], v[210:213], v[16:19]
	s_add_i32 m0, s21, 0x2400
	v_mfma_f32_16x16x32_f16 v[56:59], v[240:243], v[218:221], v[56:59]
	global_load_lds_dwordx4 v[142:143], off
	v_lshl_add_u64 v[142:143], v[142:143], 0, 64
	v_mfma_f32_16x16x32_f16 v[8:11], v[240:243], v[222:225], v[8:11]
	v_mfma_f32_16x16x32_f16 v[44:47], v[240:243], v[230:233], v[44:47]
	v_mfma_f32_16x16x32_f16 v[0:3], v[240:243], v[226:229], v[0:3]
	v_mfma_f32_16x16x32_f16 v[36:39], v[240:243], v[234:237], v[36:39]
	s_waitcnt lgkmcnt(0)
	v_mfma_f32_16x16x32_f16 v[76:79], v[244:247], v[202:205], v[76:79]
	v_mfma_f32_16x16x32_f16 v[28:31], v[244:247], v[214:217], v[28:31]
	v_mfma_f32_16x16x32_f16 v[64:67], v[244:247], v[210:213], v[64:67]
	s_add_i32 m0, s21, 0x4400
	v_mfma_f32_16x16x32_f16 v[20:23], v[244:247], v[218:221], v[20:23]
	global_load_lds_dwordx4 v[146:147], off
	v_lshl_add_u64 v[146:147], v[146:147], 0, 64
	v_mfma_f32_16x16x32_f16 v[60:63], v[244:247], v[222:225], v[60:63]
	v_mfma_f32_16x16x32_f16 v[12:15], v[244:247], v[230:233], v[12:15]
	v_mfma_f32_16x16x32_f16 v[52:55], v[244:247], v[226:229], v[52:55]
	v_mfma_f32_16x16x32_f16 v[4:7], v[244:247], v[234:237], v[4:7]
	s_add_i32 s16, s16, 1
	s_add_i32 s17, s17, 0x6000
	s_cmp_eq_u32 s17, 0x12000
	s_cselect_b32 s17, 0, s17
	s_add_i32 s20, s20, 0x6000
	s_cmp_eq_u32 s20, 0x12000
	s_cselect_b32 s20, 0, s20
	s_cmp_lt_u32 s16, 30
	s_cbranch_scc1 .Lp5a_loop
	s_waitcnt vmcnt(6)
	s_barrier
	v_add_u32_e32 v252, s17, v254
	v_add_u32_e32 v253, s17, v181
	ds_read_b128 v[198:201], v252
	ds_read_b128 v[202:205], v253 offset:8192
	ds_read_b128 v[214:217], v253 offset:16384
	ds_read_b128 v[210:213], v253 offset:9216
	ds_read_b128 v[218:221], v253 offset:17408
	ds_read_b128 v[222:225], v253 offset:10240
	ds_read_b128 v[230:233], v253 offset:18432
	ds_read_b128 v[226:229], v253 offset:11264
	ds_read_b128 v[234:237], v253 offset:19456
	ds_read_b128 v[206:209], v252 offset:1024
	s_waitcnt lgkmcnt(8)
	v_mfma_f32_16x16x32_f16 v[108:111], v[198:201], v[202:205], v[108:111]
	s_waitcnt lgkmcnt(7)
	v_mfma_f32_16x16x32_f16 v[124:127], v[198:201], v[214:217], v[124:127]
	s_waitcnt lgkmcnt(6)
	v_mfma_f32_16x16x32_f16 v[104:107], v[198:201], v[210:213], v[104:107]
	s_waitcnt lgkmcnt(5)
	v_mfma_f32_16x16x32_f16 v[120:123], v[198:201], v[218:221], v[120:123]
	s_waitcnt lgkmcnt(4)
	v_mfma_f32_16x16x32_f16 v[96:99], v[198:201], v[222:225], v[96:99]
	s_waitcnt lgkmcnt(3)
	v_mfma_f32_16x16x32_f16 v[116:119], v[198:201], v[230:233], v[116:119]
	s_waitcnt lgkmcnt(2)
	v_mfma_f32_16x16x32_f16 v[80:83], v[198:201], v[226:229], v[80:83]
	s_waitcnt lgkmcnt(1)
	v_mfma_f32_16x16x32_f16 v[112:115], v[198:201], v[234:237], v[112:115]
	ds_read_b128 v[240:243], v252 offset:2048
	ds_read_b128 v[244:247], v252 offset:3072
	s_waitcnt lgkmcnt(2)
	v_mfma_f32_16x16x32_f16 v[68:71], v[206:209], v[202:205], v[68:71]
	v_mfma_f32_16x16x32_f16 v[100:103], v[206:209], v[214:217], v[100:103]
	v_mfma_f32_16x16x32_f16 v[48:51], v[206:209], v[210:213], v[48:51]
	v_mfma_f32_16x16x32_f16 v[92:95], v[206:209], v[218:221], v[92:95]
	v_mfma_f32_16x16x32_f16 v[40:43], v[206:209], v[222:225], v[40:43]
	v_mfma_f32_16x16x32_f16 v[88:91], v[206:209], v[230:233], v[88:91]
	v_mfma_f32_16x16x32_f16 v[32:35], v[206:209], v[226:229], v[32:35]
	v_mfma_f32_16x16x32_f16 v[84:87], v[206:209], v[234:237], v[84:87]
	s_waitcnt lgkmcnt(1)
	v_mfma_f32_16x16x32_f16 v[24:27], v[240:243], v[202:205], v[24:27]
	v_mfma_f32_16x16x32_f16 v[72:75], v[240:243], v[214:217], v[72:75]
	v_mfma_f32_16x16x32_f16 v[16:19], v[240:243], v[210:213], v[16:19]
	v_mfma_f32_16x16x32_f16 v[56:59], v[240:243], v[218:221], v[56:59]
	v_mfma_f32_16x16x32_f16 v[8:11], v[240:243], v[222:225], v[8:11]
	v_mfma_f32_16x16x32_f16 v[44:47], v[240:243], v[230:233], v[44:47]
	v_mfma_f32_16x16x32_f16 v[0:3], v[240:243], v[226:229], v[0:3]
	v_mfma_f32_16x16x32_f16 v[36:39], v[240:243], v[234:237], v[36:39]
	s_waitcnt lgkmcnt(0)
	v_mfma_f32_16x16x32_f16 v[76:79], v[244:247], v[202:205], v[76:79]
	v_mfma_f32_16x16x32_f16 v[28:31], v[244:247], v[214:217], v[28:31]
	v_mfma_f32_16x16x32_f16 v[64:67], v[244:247], v[210:213], v[64:67]
	v_mfma_f32_16x16x32_f16 v[20:23], v[244:247], v[218:221], v[20:23]
	v_mfma_f32_16x16x32_f16 v[60:63], v[244:247], v[222:225], v[60:63]
	v_mfma_f32_16x16x32_f16 v[12:15], v[244:247], v[230:233], v[12:15]
	v_mfma_f32_16x16x32_f16 v[52:55], v[244:247], v[226:229], v[52:55]
	v_mfma_f32_16x16x32_f16 v[4:7], v[244:247], v[234:237], v[4:7]
	s_add_i32 s17, s17, 0x6000
	s_cmp_eq_u32 s17, 0x12000
	s_cselect_b32 s17, 0, s17
	s_waitcnt vmcnt(0)
	s_barrier
	v_add_u32_e32 v252, s17, v254
	v_add_u32_e32 v253, s17, v181
	ds_read_b128 v[198:201], v252
	ds_read_b128 v[202:205], v253 offset:8192
	ds_read_b128 v[214:217], v253 offset:16384
	ds_read_b128 v[210:213], v253 offset:9216
	ds_read_b128 v[218:221], v253 offset:17408
	ds_read_b128 v[222:225], v253 offset:10240
	ds_read_b128 v[230:233], v253 offset:18432
	ds_read_b128 v[226:229], v253 offset:11264
	ds_read_b128 v[234:237], v253 offset:19456
	ds_read_b128 v[206:209], v252 offset:1024
	s_waitcnt lgkmcnt(8)
	v_mfma_f32_16x16x32_f16 v[108:111], v[198:201], v[202:205], v[108:111]
	s_waitcnt lgkmcnt(7)
	v_mfma_f32_16x16x32_f16 v[124:127], v[198:201], v[214:217], v[124:127]
	s_waitcnt lgkmcnt(6)
	v_mfma_f32_16x16x32_f16 v[104:107], v[198:201], v[210:213], v[104:107]
	s_waitcnt lgkmcnt(5)
	v_mfma_f32_16x16x32_f16 v[120:123], v[198:201], v[218:221], v[120:123]
	s_waitcnt lgkmcnt(4)
	v_mfma_f32_16x16x32_f16 v[96:99], v[198:201], v[222:225], v[96:99]
	s_waitcnt lgkmcnt(3)
	v_mfma_f32_16x16x32_f16 v[116:119], v[198:201], v[230:233], v[116:119]
	s_waitcnt lgkmcnt(2)
	v_mfma_f32_16x16x32_f16 v[80:83], v[198:201], v[226:229], v[80:83]
	s_waitcnt lgkmcnt(1)
	v_mfma_f32_16x16x32_f16 v[112:115], v[198:201], v[234:237], v[112:115]
	ds_read_b128 v[240:243], v252 offset:2048
	ds_read_b128 v[244:247], v252 offset:3072
	s_waitcnt lgkmcnt(2)
	v_mfma_f32_16x16x32_f16 v[68:71], v[206:209], v[202:205], v[68:71]
	v_mfma_f32_16x16x32_f16 v[100:103], v[206:209], v[214:217], v[100:103]
	v_mfma_f32_16x16x32_f16 v[48:51], v[206:209], v[210:213], v[48:51]
	v_mfma_f32_16x16x32_f16 v[92:95], v[206:209], v[218:221], v[92:95]
	v_mfma_f32_16x16x32_f16 v[40:43], v[206:209], v[222:225], v[40:43]
	v_mfma_f32_16x16x32_f16 v[88:91], v[206:209], v[230:233], v[88:91]
	v_mfma_f32_16x16x32_f16 v[32:35], v[206:209], v[226:229], v[32:35]
	v_mfma_f32_16x16x32_f16 v[84:87], v[206:209], v[234:237], v[84:87]
	s_waitcnt lgkmcnt(1)
	v_mfma_f32_16x16x32_f16 v[24:27], v[240:243], v[202:205], v[24:27]
	v_mfma_f32_16x16x32_f16 v[72:75], v[240:243], v[214:217], v[72:75]
	v_mfma_f32_16x16x32_f16 v[16:19], v[240:243], v[210:213], v[16:19]
	v_mfma_f32_16x16x32_f16 v[56:59], v[240:243], v[218:221], v[56:59]
	v_mfma_f32_16x16x32_f16 v[8:11], v[240:243], v[222:225], v[8:11]
	v_mfma_f32_16x16x32_f16 v[44:47], v[240:243], v[230:233], v[44:47]
	v_mfma_f32_16x16x32_f16 v[0:3], v[240:243], v[226:229], v[0:3]
	v_mfma_f32_16x16x32_f16 v[36:39], v[240:243], v[234:237], v[36:39]
	s_waitcnt lgkmcnt(0)
	v_mfma_f32_16x16x32_f16 v[76:79], v[244:247], v[202:205], v[76:79]
	v_mfma_f32_16x16x32_f16 v[28:31], v[244:247], v[214:217], v[28:31]
	v_mfma_f32_16x16x32_f16 v[64:67], v[244:247], v[210:213], v[64:67]
	v_mfma_f32_16x16x32_f16 v[20:23], v[244:247], v[218:221], v[20:23]
	v_mfma_f32_16x16x32_f16 v[60:63], v[244:247], v[222:225], v[60:63]
	v_mfma_f32_16x16x32_f16 v[12:15], v[244:247], v[230:233], v[12:15]
	v_mfma_f32_16x16x32_f16 v[52:55], v[244:247], v[226:229], v[52:55]
	v_mfma_f32_16x16x32_f16 v[4:7], v[244:247], v[234:237], v[4:7]
	s_nop 7
	s_barrier
	v_lshrrev_b32_e32 v240, 1, v154
	v_and_b32_e32 v241, 1, v154
	v_lshlrev_b32_e32 v240, 14, v240
	v_lshrrev_b32_e32 v242, 4, v152
	v_lshl_or_b32 v240, v241, 7, v240
	v_and_b32_e32 v241, 15, v152
	v_lshl_or_b32 v240, v242, 10, v240
	s_nop 0
	v_lshl_or_b32 v240, v241, 1, v240
	v_cvt_f16_f32_e32 v108, v108
	v_cvt_f16_f32_e32 v109, v109
	v_cvt_f16_f32_e32 v110, v110
	v_cvt_f16_f32_e32 v111, v111
	ds_write_b16 v240, v108 offset:0
	ds_write_b16 v240, v109 offset:256
	ds_write_b16 v240, v110 offset:512
	ds_write_b16 v240, v111 offset:768
	v_cvt_f16_f32_e32 v104, v104
	v_cvt_f16_f32_e32 v105, v105
	v_cvt_f16_f32_e32 v106, v106
	v_cvt_f16_f32_e32 v107, v107
	ds_write_b16 v240, v104 offset:32
	ds_write_b16 v240, v105 offset:288
	ds_write_b16 v240, v106 offset:544
	ds_write_b16 v240, v107 offset:800
	v_cvt_f16_f32_e32 v96, v96
	v_cvt_f16_f32_e32 v97, v97
	v_cvt_f16_f32_e32 v98, v98
	v_cvt_f16_f32_e32 v99, v99
	ds_write_b16 v240, v96 offset:64
	ds_write_b16 v240, v97 offset:320
	ds_write_b16 v240, v98 offset:576
	ds_write_b16 v240, v99 offset:832
	v_cvt_f16_f32_e32 v80, v80
	v_cvt_f16_f32_e32 v81, v81
	v_cvt_f16_f32_e32 v82, v82
	v_cvt_f16_f32_e32 v83, v83
	ds_write_b16 v240, v80 offset:96
	ds_write_b16 v240, v81 offset:352
	ds_write_b16 v240, v82 offset:608
	ds_write_b16 v240, v83 offset:864
	v_cvt_f16_f32_e32 v68, v68
	v_cvt_f16_f32_e32 v69, v69
	v_cvt_f16_f32_e32 v70, v70
	v_cvt_f16_f32_e32 v71, v71
	ds_write_b16 v240, v68 offset:4096
	ds_write_b16 v240, v69 offset:4352
	ds_write_b16 v240, v70 offset:4608
	ds_write_b16 v240, v71 offset:4864
	v_cvt_f16_f32_e32 v48, v48
	v_cvt_f16_f32_e32 v49, v49
	v_cvt_f16_f32_e32 v50, v50
	v_cvt_f16_f32_e32 v51, v51
	ds_write_b16 v240, v48 offset:4128
	ds_write_b16 v240, v49 offset:4384
	ds_write_b16 v240, v50 offset:4640
	ds_write_b16 v240, v51 offset:4896
	v_cvt_f16_f32_e32 v40, v40
	v_cvt_f16_f32_e32 v41, v41
	v_cvt_f16_f32_e32 v42, v42
	v_cvt_f16_f32_e32 v43, v43
	ds_write_b16 v240, v40 offset:4160
	ds_write_b16 v240, v41 offset:4416
	ds_write_b16 v240, v42 offset:4672
	ds_write_b16 v240, v43 offset:4928
	v_cvt_f16_f32_e32 v32, v32
	v_cvt_f16_f32_e32 v33, v33
	v_cvt_f16_f32_e32 v34, v34
	v_cvt_f16_f32_e32 v35, v35
	ds_write_b16 v240, v32 offset:4192
	ds_write_b16 v240, v33 offset:4448
	ds_write_b16 v240, v34 offset:4704
	ds_write_b16 v240, v35 offset:4960
	v_cvt_f16_f32_e32 v24, v24
	v_cvt_f16_f32_e32 v25, v25
	v_cvt_f16_f32_e32 v26, v26
	v_cvt_f16_f32_e32 v27, v27
	ds_write_b16 v240, v24 offset:8192
	ds_write_b16 v240, v25 offset:8448
	ds_write_b16 v240, v26 offset:8704
	ds_write_b16 v240, v27 offset:8960
	v_cvt_f16_f32_e32 v16, v16
	v_cvt_f16_f32_e32 v17, v17
	v_cvt_f16_f32_e32 v18, v18
	v_cvt_f16_f32_e32 v19, v19
	ds_write_b16 v240, v16 offset:8224
	ds_write_b16 v240, v17 offset:8480
	ds_write_b16 v240, v18 offset:8736
	ds_write_b16 v240, v19 offset:8992
	v_cvt_f16_f32_e32 v8, v8
	v_cvt_f16_f32_e32 v9, v9
	v_cvt_f16_f32_e32 v10, v10
	v_cvt_f16_f32_e32 v11, v11
	ds_write_b16 v240, v8 offset:8256
	ds_write_b16 v240, v9 offset:8512
	ds_write_b16 v240, v10 offset:8768
	ds_write_b16 v240, v11 offset:9024
	v_cvt_f16_f32_e32 v0, v0
	v_cvt_f16_f32_e32 v1, v1
	v_cvt_f16_f32_e32 v2, v2
	v_cvt_f16_f32_e32 v3, v3
	ds_write_b16 v240, v0 offset:8288
	ds_write_b16 v240, v1 offset:8544
	ds_write_b16 v240, v2 offset:8800
	ds_write_b16 v240, v3 offset:9056
	v_cvt_f16_f32_e32 v76, v76
	v_cvt_f16_f32_e32 v77, v77
	v_cvt_f16_f32_e32 v78, v78
	v_cvt_f16_f32_e32 v79, v79
	ds_write_b16 v240, v76 offset:12288
	ds_write_b16 v240, v77 offset:12544
	ds_write_b16 v240, v78 offset:12800
	ds_write_b16 v240, v79 offset:13056
	v_cvt_f16_f32_e32 v64, v64
	v_cvt_f16_f32_e32 v65, v65
	v_cvt_f16_f32_e32 v66, v66
	v_cvt_f16_f32_e32 v67, v67
	ds_write_b16 v240, v64 offset:12320
	ds_write_b16 v240, v65 offset:12576
	ds_write_b16 v240, v66 offset:12832
	ds_write_b16 v240, v67 offset:13088
	v_cvt_f16_f32_e32 v60, v60
	v_cvt_f16_f32_e32 v61, v61
	v_cvt_f16_f32_e32 v62, v62
	v_cvt_f16_f32_e32 v63, v63
	ds_write_b16 v240, v60 offset:12352
	ds_write_b16 v240, v61 offset:12608
	ds_write_b16 v240, v62 offset:12864
	ds_write_b16 v240, v63 offset:13120
	v_cvt_f16_f32_e32 v52, v52
	v_cvt_f16_f32_e32 v53, v53
	v_cvt_f16_f32_e32 v54, v54
	v_cvt_f16_f32_e32 v55, v55
	ds_write_b16 v240, v52 offset:12384
	ds_write_b16 v240, v53 offset:12640
	ds_write_b16 v240, v54 offset:12896
	ds_write_b16 v240, v55 offset:13152
	v_cvt_f16_f32_e32 v124, v124
	v_cvt_f16_f32_e32 v125, v125
	v_cvt_f16_f32_e32 v126, v126
	v_cvt_f16_f32_e32 v127, v127
	ds_write_b16 v240, v124 offset:32768
	ds_write_b16 v240, v125 offset:33024
	ds_write_b16 v240, v126 offset:33280
	ds_write_b16 v240, v127 offset:33536
	v_cvt_f16_f32_e32 v120, v120
	v_cvt_f16_f32_e32 v121, v121
	v_cvt_f16_f32_e32 v122, v122
	v_cvt_f16_f32_e32 v123, v123
	ds_write_b16 v240, v120 offset:32800
	ds_write_b16 v240, v121 offset:33056
	ds_write_b16 v240, v122 offset:33312
	ds_write_b16 v240, v123 offset:33568
	v_cvt_f16_f32_e32 v116, v116
	v_cvt_f16_f32_e32 v117, v117
	v_cvt_f16_f32_e32 v118, v118
	v_cvt_f16_f32_e32 v119, v119
	ds_write_b16 v240, v116 offset:32832
	ds_write_b16 v240, v117 offset:33088
	ds_write_b16 v240, v118 offset:33344
	ds_write_b16 v240, v119 offset:33600
	v_cvt_f16_f32_e32 v112, v112
	v_cvt_f16_f32_e32 v113, v113
	v_cvt_f16_f32_e32 v114, v114
	v_cvt_f16_f32_e32 v115, v115
	ds_write_b16 v240, v112 offset:32864
	ds_write_b16 v240, v113 offset:33120
	ds_write_b16 v240, v114 offset:33376
	ds_write_b16 v240, v115 offset:33632
	v_cvt_f16_f32_e32 v100, v100
	v_cvt_f16_f32_e32 v101, v101
	v_cvt_f16_f32_e32 v102, v102
	v_cvt_f16_f32_e32 v103, v103
	ds_write_b16 v240, v100 offset:36864
	ds_write_b16 v240, v101 offset:37120
	ds_write_b16 v240, v102 offset:37376
	ds_write_b16 v240, v103 offset:37632
	v_cvt_f16_f32_e32 v92, v92
	v_cvt_f16_f32_e32 v93, v93
	v_cvt_f16_f32_e32 v94, v94
	v_cvt_f16_f32_e32 v95, v95
	ds_write_b16 v240, v92 offset:36896
	ds_write_b16 v240, v93 offset:37152
	ds_write_b16 v240, v94 offset:37408
	ds_write_b16 v240, v95 offset:37664
	v_cvt_f16_f32_e32 v88, v88
	v_cvt_f16_f32_e32 v89, v89
	v_cvt_f16_f32_e32 v90, v90
	v_cvt_f16_f32_e32 v91, v91
	ds_write_b16 v240, v88 offset:36928
	ds_write_b16 v240, v89 offset:37184
	ds_write_b16 v240, v90 offset:37440
	ds_write_b16 v240, v91 offset:37696
	v_cvt_f16_f32_e32 v84, v84
	v_cvt_f16_f32_e32 v85, v85
	v_cvt_f16_f32_e32 v86, v86
	v_cvt_f16_f32_e32 v87, v87
	ds_write_b16 v240, v84 offset:36960
	ds_write_b16 v240, v85 offset:37216
	ds_write_b16 v240, v86 offset:37472
	ds_write_b16 v240, v87 offset:37728
	v_cvt_f16_f32_e32 v72, v72
	v_cvt_f16_f32_e32 v73, v73
	v_cvt_f16_f32_e32 v74, v74
	v_cvt_f16_f32_e32 v75, v75
	ds_write_b16 v240, v72 offset:40960
	ds_write_b16 v240, v73 offset:41216
	ds_write_b16 v240, v74 offset:41472
	ds_write_b16 v240, v75 offset:41728
	v_cvt_f16_f32_e32 v56, v56
	v_cvt_f16_f32_e32 v57, v57
	v_cvt_f16_f32_e32 v58, v58
	v_cvt_f16_f32_e32 v59, v59
	ds_write_b16 v240, v56 offset:40992
	ds_write_b16 v240, v57 offset:41248
	ds_write_b16 v240, v58 offset:41504
	ds_write_b16 v240, v59 offset:41760
	v_cvt_f16_f32_e32 v44, v44
	v_cvt_f16_f32_e32 v45, v45
	v_cvt_f16_f32_e32 v46, v46
	v_cvt_f16_f32_e32 v47, v47
	ds_write_b16 v240, v44 offset:41024
	ds_write_b16 v240, v45 offset:41280
	ds_write_b16 v240, v46 offset:41536
	ds_write_b16 v240, v47 offset:41792
	v_cvt_f16_f32_e32 v36, v36
	v_cvt_f16_f32_e32 v37, v37
	v_cvt_f16_f32_e32 v38, v38
	v_cvt_f16_f32_e32 v39, v39
	ds_write_b16 v240, v36 offset:41056
	ds_write_b16 v240, v37 offset:41312
	ds_write_b16 v240, v38 offset:41568
	ds_write_b16 v240, v39 offset:41824
	v_cvt_f16_f32_e32 v28, v28
	v_cvt_f16_f32_e32 v29, v29
	v_cvt_f16_f32_e32 v30, v30
	v_cvt_f16_f32_e32 v31, v31
	ds_write_b16 v240, v28 offset:45056
	ds_write_b16 v240, v29 offset:45312
	ds_write_b16 v240, v30 offset:45568
	ds_write_b16 v240, v31 offset:45824
	v_cvt_f16_f32_e32 v20, v20
	v_cvt_f16_f32_e32 v21, v21
	v_cvt_f16_f32_e32 v22, v22
	v_cvt_f16_f32_e32 v23, v23
	ds_write_b16 v240, v20 offset:45088
	ds_write_b16 v240, v21 offset:45344
	ds_write_b16 v240, v22 offset:45600
	ds_write_b16 v240, v23 offset:45856
	v_cvt_f16_f32_e32 v12, v12
	v_cvt_f16_f32_e32 v13, v13
	v_cvt_f16_f32_e32 v14, v14
	v_cvt_f16_f32_e32 v15, v15
	ds_write_b16 v240, v12 offset:45120
	ds_write_b16 v240, v13 offset:45376
	ds_write_b16 v240, v14 offset:45632
	ds_write_b16 v240, v15 offset:45888
	v_cvt_f16_f32_e32 v4, v4
	v_cvt_f16_f32_e32 v5, v5
	v_cvt_f16_f32_e32 v6, v6
	v_cvt_f16_f32_e32 v7, v7
	ds_write_b16 v240, v4 offset:45152
	ds_write_b16 v240, v5 offset:45408
	ds_write_b16 v240, v6 offset:45664
	ds_write_b16 v240, v7 offset:45920
	v_readlane_b32 s64, v238, 0
	v_readlane_b32 s66, v238, 2
	v_readlane_b32 s67, v238, 3
	v_readlane_b32 s65, v238, 1
	v_readlane_b32 s68, v238, 4
	v_readlane_b32 s69, v238, 5
	v_or_b32_e32 v108, s13, v128
	s_mov_b32 s8, 0
	v_ashrrev_i32_e32 v109, 31, v108
	v_lshlrev_b64 v[8:9], 2, v[108:109]
	s_nop 1
	v_lshl_add_u64 v[10:11], s[66:67], 0, v[8:9]
	v_lshl_add_u64 v[16:17], s[4:5], 0, v[8:9]
	s_waitcnt lgkmcnt(0)
	s_barrier
	global_load_dwordx4 v[0:3], v[10:11], off offset:16
	global_load_dwordx4 v[4:7], v[10:11], off
	s_nop 0
	global_load_dwordx4 v[8:11], v[16:17], off offset:16
	global_load_dwordx4 v[12:15], v[16:17], off
	v_subrev_u32_e32 v16, s12, v197
	v_readlane_b32 s70, v238, 6
	v_readlane_b32 s71, v238, 7
	v_readlane_b32 s72, v238, 8
	v_readlane_b32 s73, v238, 9
	v_readlane_b32 s74, v238, 10
	v_readlane_b32 s75, v238, 11
	v_readlane_b32 s76, v238, 12
	v_readlane_b32 s77, v238, 13
	v_readlane_b32 s78, v238, 14
	v_readlane_b32 s79, v238, 15
	s_waitcnt vmcnt(0)

.LBB0_1076:
	s_mul_hi_i32 s12, s11, 0xf6603d99
	s_add_i32 s12, s12, s11
	s_lshr_b32 s13, s12, 31
	s_ashr_i32 s12, s12, 7
	s_add_i32 s13, s12, s13
	s_mul_i32 s12, s13, 0xffffff7b
	s_add_i32 s12, s12, s11
	s_lshl_b32 s21, s12, 7
	v_add_u32_e32 v0, s21, v129
	v_med3_i32 v0, v0, 0, v174
	s_lshl_b32 s20, s13, 8
	s_mul_i32 s12, s13, 0x160000
	v_mul_u32_u24_e32 v0, 0xb00, v0
	s_mul_hi_i32 s19, s20, 0x1600
	s_add_u32 s18, s3, s12
	v_or_b32_e32 v132, v0, v148
	v_add_u32_e32 v0, s21, v149
	s_addc_u32 s19, s7, s19
	s_or_b32 s12, s20, 0x80
	v_med3_i32 v0, v0, 0, v174
	v_lshlrev_b64 v[2:3], 1, v[132:133]
	v_readfirstlane_b32 s21, v150
	s_mul_i32 s22, s12, 0x1600
	v_mul_u32_u24_e32 v0, 0xb00, v0
	v_lshl_add_u64 v[4:5], s[60:61], 0, v[2:3]
	s_mov_b32 m0, s21
	v_readfirstlane_b32 s21, v176
	s_mul_hi_i32 s23, s12, 0x1600
	s_add_u32 s22, s3, s22
	v_or_b32_e32 v0, v0, v148
	global_load_lds_dwordx4 v[4:5], off
	s_mov_b32 m0, s21
	v_readfirstlane_b32 s21, v177
	v_mov_b32_e32 v1, v133
	s_addc_u32 s23, s7, s23
	global_load_lds_dwordx4 v175, s[18:19]
	s_mov_b32 m0, s21
	v_lshlrev_b64 v[0:1], 1, v[0:1]
	v_readfirstlane_b32 s21, v178
	global_load_lds_dwordx4 v175, s[22:23]
	v_lshl_add_u64 v[4:5], s[60:61], 0, v[0:1]
	s_mov_b32 m0, s21
	v_lshl_add_u64 v[140:141], s[4:5], 0, v[2:3]
	global_load_lds_dwordx4 v[4:5], off
	v_lshl_add_u64 v[4:5], s[18:19], 0, v[138:139]
	v_readfirstlane_b32 s18, v179
	s_mov_b32 m0, s18
	v_readfirstlane_b32 s18, v180
	global_load_lds_dwordx4 v[4:5], off
	v_lshl_add_u64 v[4:5], s[22:23], 0, v[138:139]
	s_mov_b32 m0, s18
	v_mad_i64_i32 v[144:145], s[18:19], s20, v181, v[134:135]
	global_load_lds_dwordx4 v[4:5], off
	v_mad_i64_i32 v[146:147], s[18:19], s20, v181, v[136:137]
	v_lshl_add_u64 v[142:143], s[4:5], 0, v[0:1]
	v_lshl_add_u64 v[248:249], v[144:145], 0, s[14:15]
	v_lshl_add_u64 v[250:251], v[146:147], 0, s[14:15]
	v_lshl_add_u64 v[144:145], v[144:145], 0, s[8:9]
	v_lshl_add_u64 v[146:147], v[146:147], 0, s[8:9]
	v_add_u32_e32 v254, v151, v166
	v_readfirstlane_b32 s25, v150
	s_add_i32 s24, s25, 0x6000
	s_mov_b32 m0, s24
	s_nop 0
	global_load_lds_dwordx4 v[140:141], off
	v_lshl_add_u64 v[140:141], v[140:141], 0, 64
	s_add_i32 m0, s24, 0x2000
	s_nop 0
	global_load_lds_dwordx4 v[144:145], off
	v_lshl_add_u64 v[144:145], v[144:145], 0, 64
	s_add_i32 m0, s24, 0x4000
	s_nop 0
	global_load_lds_dwordx4 v[248:249], off
	v_lshl_add_u64 v[248:249], v[248:249], 0, 64
	s_add_i32 m0, s24, 0x400
	s_nop 0
	global_load_lds_dwordx4 v[142:143], off
	v_lshl_add_u64 v[142:143], v[142:143], 0, 64
	s_add_i32 m0, s24, 0x2400
	s_nop 0
	global_load_lds_dwordx4 v[146:147], off
	v_lshl_add_u64 v[146:147], v[146:147], 0, 64
	s_add_i32 m0, s24, 0x4400
	s_nop 0
	global_load_lds_dwordx4 v[250:251], off
	v_lshl_add_u64 v[250:251], v[250:251], 0, 64
	v_mov_b32_e32 v0, 0
	v_mov_b32_e32 v1, 0
	v_mov_b32_e32 v2, 0
	v_mov_b32_e32 v3, 0
	v_mov_b32_e32 v4, 0
	v_mov_b32_e32 v5, 0
	v_mov_b32_e32 v6, 0
	v_mov_b32_e32 v7, 0
	v_mov_b32_e32 v8, 0
	v_mov_b32_e32 v9, 0
	v_mov_b32_e32 v10, 0
	v_mov_b32_e32 v11, 0
	v_mov_b32_e32 v12, 0
	v_mov_b32_e32 v13, 0
	v_mov_b32_e32 v14, 0
	v_mov_b32_e32 v15, 0
	v_mov_b32_e32 v16, 0
	v_mov_b32_e32 v17, 0
	v_mov_b32_e32 v18, 0
	v_mov_b32_e32 v19, 0
	v_mov_b32_e32 v20, 0
	v_mov_b32_e32 v21, 0
	v_mov_b32_e32 v22, 0
	v_mov_b32_e32 v23, 0
	v_mov_b32_e32 v24, 0
	v_mov_b32_e32 v25, 0
	v_mov_b32_e32 v26, 0
	v_mov_b32_e32 v27, 0
	v_mov_b32_e32 v28, 0
	v_mov_b32_e32 v29, 0
	v_mov_b32_e32 v30, 0
	v_mov_b32_e32 v31, 0
	v_mov_b32_e32 v32, 0
	v_mov_b32_e32 v33, 0
	v_mov_b32_e32 v34, 0
	v_mov_b32_e32 v35, 0
	v_mov_b32_e32 v36, 0
	v_mov_b32_e32 v37, 0
	v_mov_b32_e32 v38, 0
	v_mov_b32_e32 v39, 0
	v_mov_b32_e32 v40, 0
	v_mov_b32_e32 v41, 0
	v_mov_b32_e32 v42, 0
	v_mov_b32_e32 v43, 0
	v_mov_b32_e32 v44, 0
	v_mov_b32_e32 v45, 0
	v_mov_b32_e32 v46, 0
	v_mov_b32_e32 v47, 0
	v_mov_b32_e32 v48, 0
	v_mov_b32_e32 v49, 0
	v_mov_b32_e32 v50, 0
	v_mov_b32_e32 v51, 0
	v_mov_b32_e32 v52, 0
	v_mov_b32_e32 v53, 0
	v_mov_b32_e32 v54, 0
	v_mov_b32_e32 v55, 0
	v_mov_b32_e32 v56, 0
	v_mov_b32_e32 v57, 0
	v_mov_b32_e32 v58, 0
	v_mov_b32_e32 v59, 0
	v_mov_b32_e32 v60, 0
	v_mov_b32_e32 v61, 0
	v_mov_b32_e32 v62, 0
	v_mov_b32_e32 v63, 0
	v_mov_b32_e32 v64, 0
	v_mov_b32_e32 v65, 0
	v_mov_b32_e32 v66, 0
	v_mov_b32_e32 v67, 0
	v_mov_b32_e32 v68, 0
	v_mov_b32_e32 v69, 0
	v_mov_b32_e32 v70, 0
	v_mov_b32_e32 v71, 0
	v_mov_b32_e32 v72, 0
	v_mov_b32_e32 v73, 0
	v_mov_b32_e32 v74, 0
	v_mov_b32_e32 v75, 0
	v_mov_b32_e32 v76, 0
	v_mov_b32_e32 v77, 0
	v_mov_b32_e32 v78, 0
	v_mov_b32_e32 v79, 0
	v_mov_b32_e32 v80, 0
	v_mov_b32_e32 v81, 0
	v_mov_b32_e32 v82, 0
	v_mov_b32_e32 v83, 0
	v_mov_b32_e32 v84, 0
	v_mov_b32_e32 v85, 0
	v_mov_b32_e32 v86, 0
	v_mov_b32_e32 v87, 0
	v_mov_b32_e32 v88, 0
	v_mov_b32_e32 v89, 0
	v_mov_b32_e32 v90, 0
	v_mov_b32_e32 v91, 0
	v_mov_b32_e32 v92, 0
	v_mov_b32_e32 v93, 0
	v_mov_b32_e32 v94, 0
	v_mov_b32_e32 v95, 0
	v_mov_b32_e32 v96, 0
	v_mov_b32_e32 v97, 0
	v_mov_b32_e32 v98, 0
	v_mov_b32_e32 v99, 0
	v_mov_b32_e32 v100, 0
	v_mov_b32_e32 v101, 0
	v_mov_b32_e32 v102, 0
	v_mov_b32_e32 v103, 0
	v_mov_b32_e32 v104, 0
	v_mov_b32_e32 v105, 0
	v_mov_b32_e32 v106, 0
	v_mov_b32_e32 v107, 0
	v_mov_b32_e32 v108, 0
	v_mov_b32_e32 v109, 0
	v_mov_b32_e32 v110, 0
	v_mov_b32_e32 v111, 0
	v_mov_b32_e32 v112, 0
	v_mov_b32_e32 v113, 0
	v_mov_b32_e32 v114, 0
	v_mov_b32_e32 v115, 0
	v_mov_b32_e32 v116, 0
	v_mov_b32_e32 v117, 0
	v_mov_b32_e32 v118, 0
	v_mov_b32_e32 v119, 0
	v_mov_b32_e32 v120, 0
	v_mov_b32_e32 v121, 0
	v_mov_b32_e32 v122, 0
	v_mov_b32_e32 v123, 0
	v_mov_b32_e32 v124, 0
	v_mov_b32_e32 v125, 0
	v_mov_b32_e32 v126, 0
	v_mov_b32_e32 v127, 0
	s_mov_b32 s21, 0
	s_mov_b32 s22, 0
	s_mov_b32 s23, 0xc000
.Lp9_loop:
	s_waitcnt vmcnt(6)
	s_barrier
	v_add_u32_e32 v252, s22, v254
	v_add_u32_e32 v253, s22, v167
	s_add_i32 s24, s25, s23
	ds_read_b128 v[182:185], v252
	ds_read_b128 v[186:189], v253 offset:8192
	ds_read_b128 v[198:201], v253 offset:16384
	ds_read_b128 v[194:197], v253 offset:9216
	ds_read_b128 v[202:205], v253 offset:17408
	ds_read_b128 v[206:209], v253 offset:10240
	ds_read_b128 v[214:217], v253 offset:18432
	ds_read_b128 v[210:213], v253 offset:11264
	ds_read_b128 v[218:221], v253 offset:19456
	ds_read_b128 v[190:193], v252 offset:1024
	s_mov_b32 m0, s24
	s_nop 0
	global_load_lds_dwordx4 v[140:141], off
	v_lshl_add_u64 v[140:141], v[140:141], 0, 64
	s_add_i32 m0, s24, 0x2000
	s_nop 0
	global_load_lds_dwordx4 v[144:145], off
	v_lshl_add_u64 v[144:145], v[144:145], 0, 64
	s_waitcnt lgkmcnt(8)
	v_mfma_f32_16x16x32_f16 v[108:111], v[182:185], v[186:189], v[108:111]
	s_waitcnt lgkmcnt(7)
	v_mfma_f32_16x16x32_f16 v[124:127], v[182:185], v[198:201], v[124:127]
	s_waitcnt lgkmcnt(6)
	v_mfma_f32_16x16x32_f16 v[104:107], v[182:185], v[194:197], v[104:107]
	s_add_i32 m0, s24, 0x4000
	s_waitcnt lgkmcnt(5)
	v_mfma_f32_16x16x32_f16 v[120:123], v[182:185], v[202:205], v[120:123]
	global_load_lds_dwordx4 v[248:249], off
	v_lshl_add_u64 v[248:249], v[248:249], 0, 64
	s_waitcnt lgkmcnt(4)
	v_mfma_f32_16x16x32_f16 v[96:99], v[182:185], v[206:209], v[96:99]
	s_waitcnt lgkmcnt(3)
	v_mfma_f32_16x16x32_f16 v[116:119], v[182:185], v[214:217], v[116:119]
	s_waitcnt lgkmcnt(2)
	v_mfma_f32_16x16x32_f16 v[80:83], v[182:185], v[210:213], v[80:83]
	s_waitcnt lgkmcnt(1)
	v_mfma_f32_16x16x32_f16 v[112:115], v[182:185], v[218:221], v[112:115]
	ds_read_b128 v[240:243], v252 offset:2048
	ds_read_b128 v[244:247], v252 offset:3072
	s_waitcnt lgkmcnt(2)
	v_mfma_f32_16x16x32_f16 v[72:75], v[190:193], v[186:189], v[72:75]
	v_mfma_f32_16x16x32_f16 v[100:103], v[190:193], v[198:201], v[100:103]
	v_mfma_f32_16x16x32_f16 v[64:67], v[190:193], v[194:197], v[64:67]
	s_add_i32 m0, s24, 0x400
	v_mfma_f32_16x16x32_f16 v[92:95], v[190:193], v[202:205], v[92:95]
	global_load_lds_dwordx4 v[142:143], off
	v_lshl_add_u64 v[142:143], v[142:143], 0, 64
	v_mfma_f32_16x16x32_f16 v[56:59], v[190:193], v[206:209], v[56:59]
	v_mfma_f32_16x16x32_f16 v[88:91], v[190:193], v[214:217], v[88:91]
	v_mfma_f32_16x16x32_f16 v[48:51], v[190:193], v[210:213], v[48:51]
	v_mfma_f32_16x16x32_f16 v[84:87], v[190:193], v[218:221], v[84:87]
	s_waitcnt lgkmcnt(1)
	v_mfma_f32_16x16x32_f16 v[40:43], v[240:243], v[186:189], v[40:43]
	v_mfma_f32_16x16x32_f16 v[76:79], v[240:243], v[198:201], v[76:79]
	v_mfma_f32_16x16x32_f16 v[32:35], v[240:243], v[194:197], v[32:35]
	s_add_i32 m0, s24, 0x2400
	v_mfma_f32_16x16x32_f16 v[68:71], v[240:243], v[202:205], v[68:71]
	global_load_lds_dwordx4 v[146:147], off
	v_lshl_add_u64 v[146:147], v[146:147], 0, 64
	v_mfma_f32_16x16x32_f16 v[24:27], v[240:243], v[206:209], v[24:27]
	v_mfma_f32_16x16x32_f16 v[60:63], v[240:243], v[214:217], v[60:63]
	v_mfma_f32_16x16x32_f16 v[16:19], v[240:243], v[210:213], v[16:19]
	v_mfma_f32_16x16x32_f16 v[52:55], v[240:243], v[218:221], v[52:55]
	s_waitcnt lgkmcnt(0)
	v_mfma_f32_16x16x32_f16 v[12:15], v[244:247], v[186:189], v[12:15]
	v_mfma_f32_16x16x32_f16 v[44:47], v[244:247], v[198:201], v[44:47]
	v_mfma_f32_16x16x32_f16 v[8:11], v[244:247], v[194:197], v[8:11]
	s_add_i32 m0, s24, 0x4400
	v_mfma_f32_16x16x32_f16 v[36:39], v[244:247], v[202:205], v[36:39]
	global_load_lds_dwordx4 v[250:251], off
	v_lshl_add_u64 v[250:251], v[250:251], 0, 64
	v_mfma_f32_16x16x32_f16 v[4:7], v[244:247], v[206:209], v[4:7]
	v_mfma_f32_16x16x32_f16 v[28:31], v[244:247], v[214:217], v[28:31]
	v_mfma_f32_16x16x32_f16 v[0:3], v[244:247], v[210:213], v[0:3]
	v_mfma_f32_16x16x32_f16 v[20:23], v[244:247], v[218:221], v[20:23]
	s_add_i32 s21, s21, 1
	s_add_i32 s22, s22, 0x6000
	s_cmp_eq_u32 s22, 0x12000
	s_cselect_b32 s22, 0, s22
	s_add_i32 s23, s23, 0x6000
	s_cmp_eq_u32 s23, 0x12000
	s_cselect_b32 s23, 0, s23
	s_cmp_lt_u32 s21, 86
	s_cbranch_scc1 .Lp9_loop
	s_waitcnt vmcnt(6)
	s_barrier
	v_add_u32_e32 v252, s22, v254
	v_add_u32_e32 v253, s22, v167
	ds_read_b128 v[182:185], v252
	ds_read_b128 v[186:189], v253 offset:8192
	ds_read_b128 v[198:201], v253 offset:16384
	ds_read_b128 v[194:197], v253 offset:9216
	ds_read_b128 v[202:205], v253 offset:17408
	ds_read_b128 v[206:209], v253 offset:10240
	ds_read_b128 v[214:217], v253 offset:18432
	ds_read_b128 v[210:213], v253 offset:11264
	ds_read_b128 v[218:221], v253 offset:19456
	ds_read_b128 v[190:193], v252 offset:1024
	s_waitcnt lgkmcnt(8)
	v_mfma_f32_16x16x32_f16 v[108:111], v[182:185], v[186:189], v[108:111]
	s_waitcnt lgkmcnt(7)
	v_mfma_f32_16x16x32_f16 v[124:127], v[182:185], v[198:201], v[124:127]
	s_waitcnt lgkmcnt(6)
	v_mfma_f32_16x16x32_f16 v[104:107], v[182:185], v[194:197], v[104:107]
	s_waitcnt lgkmcnt(5)
	v_mfma_f32_16x16x32_f16 v[120:123], v[182:185], v[202:205], v[120:123]
	s_waitcnt lgkmcnt(4)
	v_mfma_f32_16x16x32_f16 v[96:99], v[182:185], v[206:209], v[96:99]
	s_waitcnt lgkmcnt(3)
	v_mfma_f32_16x16x32_f16 v[116:119], v[182:185], v[214:217], v[116:119]
	s_waitcnt lgkmcnt(2)
	v_mfma_f32_16x16x32_f16 v[80:83], v[182:185], v[210:213], v[80:83]
	s_waitcnt lgkmcnt(1)
	v_mfma_f32_16x16x32_f16 v[112:115], v[182:185], v[218:221], v[112:115]
	ds_read_b128 v[240:243], v252 offset:2048
	ds_read_b128 v[244:247], v252 offset:3072
	s_waitcnt lgkmcnt(2)
	v_mfma_f32_16x16x32_f16 v[72:75], v[190:193], v[186:189], v[72:75]
	v_mfma_f32_16x16x32_f16 v[100:103], v[190:193], v[198:201], v[100:103]
	v_mfma_f32_16x16x32_f16 v[64:67], v[190:193], v[194:197], v[64:67]
	v_mfma_f32_16x16x32_f16 v[92:95], v[190:193], v[202:205], v[92:95]
	v_mfma_f32_16x16x32_f16 v[56:59], v[190:193], v[206:209], v[56:59]
	v_mfma_f32_16x16x32_f16 v[88:91], v[190:193], v[214:217], v[88:91]
	v_mfma_f32_16x16x32_f16 v[48:51], v[190:193], v[210:213], v[48:51]
	v_mfma_f32_16x16x32_f16 v[84:87], v[190:193], v[218:221], v[84:87]
	s_waitcnt lgkmcnt(1)
	v_mfma_f32_16x16x32_f16 v[40:43], v[240:243], v[186:189], v[40:43]
	v_mfma_f32_16x16x32_f16 v[76:79], v[240:243], v[198:201], v[76:79]
	v_mfma_f32_16x16x32_f16 v[32:35], v[240:243], v[194:197], v[32:35]
	v_mfma_f32_16x16x32_f16 v[68:71], v[240:243], v[202:205], v[68:71]
	v_mfma_f32_16x16x32_f16 v[24:27], v[240:243], v[206:209], v[24:27]
	v_mfma_f32_16x16x32_f16 v[60:63], v[240:243], v[214:217], v[60:63]
	v_mfma_f32_16x16x32_f16 v[16:19], v[240:243], v[210:213], v[16:19]
	v_mfma_f32_16x16x32_f16 v[52:55], v[240:243], v[218:221], v[52:55]
	s_waitcnt lgkmcnt(0)
	v_mfma_f32_16x16x32_f16 v[12:15], v[244:247], v[186:189], v[12:15]
	v_mfma_f32_16x16x32_f16 v[44:47], v[244:247], v[198:201], v[44:47]
	v_mfma_f32_16x16x32_f16 v[8:11], v[244:247], v[194:197], v[8:11]
	v_mfma_f32_16x16x32_f16 v[36:39], v[244:247], v[202:205], v[36:39]
	v_mfma_f32_16x16x32_f16 v[4:7], v[244:247], v[206:209], v[4:7]
	v_mfma_f32_16x16x32_f16 v[28:31], v[244:247], v[214:217], v[28:31]
	v_mfma_f32_16x16x32_f16 v[0:3], v[244:247], v[210:213], v[0:3]
	v_mfma_f32_16x16x32_f16 v[20:23], v[244:247], v[218:221], v[20:23]
	s_add_i32 s22, s22, 0x6000
	s_cmp_eq_u32 s22, 0x12000
	s_cselect_b32 s22, 0, s22
	s_waitcnt vmcnt(0)
	s_barrier
	v_add_u32_e32 v252, s22, v254
	v_add_u32_e32 v253, s22, v167
	ds_read_b128 v[182:185], v252
	ds_read_b128 v[186:189], v253 offset:8192
	ds_read_b128 v[198:201], v253 offset:16384
	ds_read_b128 v[194:197], v253 offset:9216
	ds_read_b128 v[202:205], v253 offset:17408
	ds_read_b128 v[206:209], v253 offset:10240
	ds_read_b128 v[214:217], v253 offset:18432
	ds_read_b128 v[210:213], v253 offset:11264
	ds_read_b128 v[218:221], v253 offset:19456
	ds_read_b128 v[190:193], v252 offset:1024
	s_waitcnt lgkmcnt(8)
	v_mfma_f32_16x16x32_f16 v[108:111], v[182:185], v[186:189], v[108:111]
	s_waitcnt lgkmcnt(7)
	v_mfma_f32_16x16x32_f16 v[124:127], v[182:185], v[198:201], v[124:127]
	s_waitcnt lgkmcnt(6)
	v_mfma_f32_16x16x32_f16 v[104:107], v[182:185], v[194:197], v[104:107]
	s_waitcnt lgkmcnt(5)
	v_mfma_f32_16x16x32_f16 v[120:123], v[182:185], v[202:205], v[120:123]
	s_waitcnt lgkmcnt(4)
	v_mfma_f32_16x16x32_f16 v[96:99], v[182:185], v[206:209], v[96:99]
	s_waitcnt lgkmcnt(3)
	v_mfma_f32_16x16x32_f16 v[116:119], v[182:185], v[214:217], v[116:119]
	s_waitcnt lgkmcnt(2)
	v_mfma_f32_16x16x32_f16 v[80:83], v[182:185], v[210:213], v[80:83]
	s_waitcnt lgkmcnt(1)
	v_mfma_f32_16x16x32_f16 v[112:115], v[182:185], v[218:221], v[112:115]
	ds_read_b128 v[240:243], v252 offset:2048
	ds_read_b128 v[244:247], v252 offset:3072
	s_waitcnt lgkmcnt(2)
	v_mfma_f32_16x16x32_f16 v[72:75], v[190:193], v[186:189], v[72:75]
	v_mfma_f32_16x16x32_f16 v[100:103], v[190:193], v[198:201], v[100:103]
	v_mfma_f32_16x16x32_f16 v[64:67], v[190:193], v[194:197], v[64:67]
	v_mfma_f32_16x16x32_f16 v[92:95], v[190:193], v[202:205], v[92:95]
	v_mfma_f32_16x16x32_f16 v[56:59], v[190:193], v[206:209], v[56:59]
	v_mfma_f32_16x16x32_f16 v[88:91], v[190:193], v[214:217], v[88:91]
	v_mfma_f32_16x16x32_f16 v[48:51], v[190:193], v[210:213], v[48:51]
	v_mfma_f32_16x16x32_f16 v[84:87], v[190:193], v[218:221], v[84:87]
	s_waitcnt lgkmcnt(1)
	v_mfma_f32_16x16x32_f16 v[40:43], v[240:243], v[186:189], v[40:43]
	v_mfma_f32_16x16x32_f16 v[76:79], v[240:243], v[198:201], v[76:79]
	v_mfma_f32_16x16x32_f16 v[32:35], v[240:243], v[194:197], v[32:35]
	v_mfma_f32_16x16x32_f16 v[68:71], v[240:243], v[202:205], v[68:71]
	v_mfma_f32_16x16x32_f16 v[24:27], v[240:243], v[206:209], v[24:27]
	v_mfma_f32_16x16x32_f16 v[60:63], v[240:243], v[214:217], v[60:63]
	v_mfma_f32_16x16x32_f16 v[16:19], v[240:243], v[210:213], v[16:19]
	v_mfma_f32_16x16x32_f16 v[52:55], v[240:243], v[218:221], v[52:55]
	s_waitcnt lgkmcnt(0)
	v_mfma_f32_16x16x32_f16 v[12:15], v[244:247], v[186:189], v[12:15]
	v_mfma_f32_16x16x32_f16 v[44:47], v[244:247], v[198:201], v[44:47]
	v_mfma_f32_16x16x32_f16 v[8:11], v[244:247], v[194:197], v[8:11]
	v_mfma_f32_16x16x32_f16 v[36:39], v[244:247], v[202:205], v[36:39]
	v_mfma_f32_16x16x32_f16 v[4:7], v[244:247], v[206:209], v[4:7]
	v_mfma_f32_16x16x32_f16 v[28:31], v[244:247], v[214:217], v[28:31]
	v_mfma_f32_16x16x32_f16 v[0:3], v[244:247], v[210:213], v[0:3]
	v_mfma_f32_16x16x32_f16 v[20:23], v[244:247], v[218:221], v[20:23]
	s_nop 7
	s_barrier
	v_lshrrev_b32_e32 v240, 1, v154
	v_and_b32_e32 v241, 1, v154
	v_lshlrev_b32_e32 v240, 14, v240
	v_lshrrev_b32_e32 v242, 4, v152
	v_lshl_or_b32 v240, v241, 7, v240
	v_and_b32_e32 v241, 15, v152
	v_lshl_or_b32 v240, v242, 10, v240
	s_nop 0
	v_lshl_or_b32 v240, v241, 1, v240
	v_cvt_f16_f32_e32 v108, v108
	v_cvt_f16_f32_e32 v109, v109
	v_cvt_f16_f32_e32 v110, v110
	v_cvt_f16_f32_e32 v111, v111
	ds_write_b16 v240, v108 offset:0
	ds_write_b16 v240, v109 offset:256
	ds_write_b16 v240, v110 offset:512
	ds_write_b16 v240, v111 offset:768
	v_cvt_f16_f32_e32 v104, v104
	v_cvt_f16_f32_e32 v105, v105
	v_cvt_f16_f32_e32 v106, v106
	v_cvt_f16_f32_e32 v107, v107
	ds_write_b16 v240, v104 offset:32
	ds_write_b16 v240, v105 offset:288
	ds_write_b16 v240, v106 offset:544
	ds_write_b16 v240, v107 offset:800
	v_cvt_f16_f32_e32 v96, v96
	v_cvt_f16_f32_e32 v97, v97
	v_cvt_f16_f32_e32 v98, v98
	v_cvt_f16_f32_e32 v99, v99
	ds_write_b16 v240, v96 offset:64
	ds_write_b16 v240, v97 offset:320
	ds_write_b16 v240, v98 offset:576
	ds_write_b16 v240, v99 offset:832
	v_cvt_f16_f32_e32 v80, v80
	v_cvt_f16_f32_e32 v81, v81
	v_cvt_f16_f32_e32 v82, v82
	v_cvt_f16_f32_e32 v83, v83
	ds_write_b16 v240, v80 offset:96
	ds_write_b16 v240, v81 offset:352
	ds_write_b16 v240, v82 offset:608
	ds_write_b16 v240, v83 offset:864
	v_cvt_f16_f32_e32 v72, v72
	v_cvt_f16_f32_e32 v73, v73
	v_cvt_f16_f32_e32 v74, v74
	v_cvt_f16_f32_e32 v75, v75
	ds_write_b16 v240, v72 offset:4096
	ds_write_b16 v240, v73 offset:4352
	ds_write_b16 v240, v74 offset:4608
	ds_write_b16 v240, v75 offset:4864
	v_cvt_f16_f32_e32 v64, v64
	v_cvt_f16_f32_e32 v65, v65
	v_cvt_f16_f32_e32 v66, v66
	v_cvt_f16_f32_e32 v67, v67
	ds_write_b16 v240, v64 offset:4128
	ds_write_b16 v240, v65 offset:4384
	ds_write_b16 v240, v66 offset:4640
	ds_write_b16 v240, v67 offset:4896
	v_cvt_f16_f32_e32 v56, v56
	v_cvt_f16_f32_e32 v57, v57
	v_cvt_f16_f32_e32 v58, v58
	v_cvt_f16_f32_e32 v59, v59
	ds_write_b16 v240, v56 offset:4160
	ds_write_b16 v240, v57 offset:4416
	ds_write_b16 v240, v58 offset:4672
	ds_write_b16 v240, v59 offset:4928
	v_cvt_f16_f32_e32 v48, v48
	v_cvt_f16_f32_e32 v49, v49
	v_cvt_f16_f32_e32 v50, v50
	v_cvt_f16_f32_e32 v51, v51
	ds_write_b16 v240, v48 offset:4192
	ds_write_b16 v240, v49 offset:4448
	ds_write_b16 v240, v50 offset:4704
	ds_write_b16 v240, v51 offset:4960
	v_cvt_f16_f32_e32 v40, v40
	v_cvt_f16_f32_e32 v41, v41
	v_cvt_f16_f32_e32 v42, v42
	v_cvt_f16_f32_e32 v43, v43
	ds_write_b16 v240, v40 offset:8192
	ds_write_b16 v240, v41 offset:8448
	ds_write_b16 v240, v42 offset:8704
	ds_write_b16 v240, v43 offset:8960
	v_cvt_f16_f32_e32 v32, v32
	v_cvt_f16_f32_e32 v33, v33
	v_cvt_f16_f32_e32 v34, v34
	v_cvt_f16_f32_e32 v35, v35
	ds_write_b16 v240, v32 offset:8224
	ds_write_b16 v240, v33 offset:8480
	ds_write_b16 v240, v34 offset:8736
	ds_write_b16 v240, v35 offset:8992
	v_cvt_f16_f32_e32 v24, v24
	v_cvt_f16_f32_e32 v25, v25
	v_cvt_f16_f32_e32 v26, v26
	v_cvt_f16_f32_e32 v27, v27
	ds_write_b16 v240, v24 offset:8256
	ds_write_b16 v240, v25 offset:8512
	ds_write_b16 v240, v26 offset:8768
	ds_write_b16 v240, v27 offset:9024
	v_cvt_f16_f32_e32 v16, v16
	v_cvt_f16_f32_e32 v17, v17
	v_cvt_f16_f32_e32 v18, v18
	v_cvt_f16_f32_e32 v19, v19
	ds_write_b16 v240, v16 offset:8288
	ds_write_b16 v240, v17 offset:8544
	ds_write_b16 v240, v18 offset:8800
	ds_write_b16 v240, v19 offset:9056
	v_cvt_f16_f32_e32 v12, v12
	v_cvt_f16_f32_e32 v13, v13
	v_cvt_f16_f32_e32 v14, v14
	v_cvt_f16_f32_e32 v15, v15
	ds_write_b16 v240, v12 offset:12288
	ds_write_b16 v240, v13 offset:12544
	ds_write_b16 v240, v14 offset:12800
	ds_write_b16 v240, v15 offset:13056
	v_cvt_f16_f32_e32 v8, v8
	v_cvt_f16_f32_e32 v9, v9
	v_cvt_f16_f32_e32 v10, v10
	v_cvt_f16_f32_e32 v11, v11
	ds_write_b16 v240, v8 offset:12320
	ds_write_b16 v240, v9 offset:12576
	ds_write_b16 v240, v10 offset:12832
	ds_write_b16 v240, v11 offset:13088
	v_cvt_f16_f32_e32 v4, v4
	v_cvt_f16_f32_e32 v5, v5
	v_cvt_f16_f32_e32 v6, v6
	v_cvt_f16_f32_e32 v7, v7
	ds_write_b16 v240, v4 offset:12352
	ds_write_b16 v240, v5 offset:12608
	ds_write_b16 v240, v6 offset:12864
	ds_write_b16 v240, v7 offset:13120
	v_cvt_f16_f32_e32 v0, v0
	v_cvt_f16_f32_e32 v1, v1
	v_cvt_f16_f32_e32 v2, v2
	v_cvt_f16_f32_e32 v3, v3
	ds_write_b16 v240, v0 offset:12384
	ds_write_b16 v240, v1 offset:12640
	ds_write_b16 v240, v2 offset:12896
	ds_write_b16 v240, v3 offset:13152
	v_cvt_f16_f32_e32 v124, v124
	v_cvt_f16_f32_e32 v125, v125
	v_cvt_f16_f32_e32 v126, v126
	v_cvt_f16_f32_e32 v127, v127
	ds_write_b16 v240, v124 offset:32768
	ds_write_b16 v240, v125 offset:33024
	ds_write_b16 v240, v126 offset:33280
	ds_write_b16 v240, v127 offset:33536
	v_cvt_f16_f32_e32 v120, v120
	v_cvt_f16_f32_e32 v121, v121
	v_cvt_f16_f32_e32 v122, v122
	v_cvt_f16_f32_e32 v123, v123
	ds_write_b16 v240, v120 offset:32800
	ds_write_b16 v240, v121 offset:33056
	ds_write_b16 v240, v122 offset:33312
	ds_write_b16 v240, v123 offset:33568
	v_cvt_f16_f32_e32 v116, v116
	v_cvt_f16_f32_e32 v117, v117
	v_cvt_f16_f32_e32 v118, v118
	v_cvt_f16_f32_e32 v119, v119
	ds_write_b16 v240, v116 offset:32832
	ds_write_b16 v240, v117 offset:33088
	ds_write_b16 v240, v118 offset:33344
	ds_write_b16 v240, v119 offset:33600
	v_cvt_f16_f32_e32 v112, v112
	v_cvt_f16_f32_e32 v113, v113
	v_cvt_f16_f32_e32 v114, v114
	v_cvt_f16_f32_e32 v115, v115
	ds_write_b16 v240, v112 offset:32864
	ds_write_b16 v240, v113 offset:33120
	ds_write_b16 v240, v114 offset:33376
	ds_write_b16 v240, v115 offset:33632
	v_cvt_f16_f32_e32 v100, v100
	v_cvt_f16_f32_e32 v101, v101
	v_cvt_f16_f32_e32 v102, v102
	v_cvt_f16_f32_e32 v103, v103
	ds_write_b16 v240, v100 offset:36864
	ds_write_b16 v240, v101 offset:37120
	ds_write_b16 v240, v102 offset:37376
	ds_write_b16 v240, v103 offset:37632
	v_cvt_f16_f32_e32 v92, v92
	v_cvt_f16_f32_e32 v93, v93
	v_cvt_f16_f32_e32 v94, v94
	v_cvt_f16_f32_e32 v95, v95
	ds_write_b16 v240, v92 offset:36896
	ds_write_b16 v240, v93 offset:37152
	ds_write_b16 v240, v94 offset:37408
	ds_write_b16 v240, v95 offset:37664
	v_cvt_f16_f32_e32 v88, v88
	v_cvt_f16_f32_e32 v89, v89
	v_cvt_f16_f32_e32 v90, v90
	v_cvt_f16_f32_e32 v91, v91
	ds_write_b16 v240, v88 offset:36928
	ds_write_b16 v240, v89 offset:37184
	ds_write_b16 v240, v90 offset:37440
	ds_write_b16 v240, v91 offset:37696
	v_cvt_f16_f32_e32 v84, v84
	v_cvt_f16_f32_e32 v85, v85
	v_cvt_f16_f32_e32 v86, v86
	v_cvt_f16_f32_e32 v87, v87
	ds_write_b16 v240, v84 offset:36960
	ds_write_b16 v240, v85 offset:37216
	ds_write_b16 v240, v86 offset:37472
	ds_write_b16 v240, v87 offset:37728
	v_cvt_f16_f32_e32 v76, v76
	v_cvt_f16_f32_e32 v77, v77
	v_cvt_f16_f32_e32 v78, v78
	v_cvt_f16_f32_e32 v79, v79
	ds_write_b16 v240, v76 offset:40960
	ds_write_b16 v240, v77 offset:41216
	ds_write_b16 v240, v78 offset:41472
	ds_write_b16 v240, v79 offset:41728
	v_cvt_f16_f32_e32 v68, v68
	v_cvt_f16_f32_e32 v69, v69
	v_cvt_f16_f32_e32 v70, v70
	v_cvt_f16_f32_e32 v71, v71
	ds_write_b16 v240, v68 offset:40992
	ds_write_b16 v240, v69 offset:41248
	ds_write_b16 v240, v70 offset:41504
	ds_write_b16 v240, v71 offset:41760
	v_cvt_f16_f32_e32 v60, v60
	v_cvt_f16_f32_e32 v61, v61
	v_cvt_f16_f32_e32 v62, v62
	v_cvt_f16_f32_e32 v63, v63
	ds_write_b16 v240, v60 offset:41024
	ds_write_b16 v240, v61 offset:41280
	ds_write_b16 v240, v62 offset:41536
	ds_write_b16 v240, v63 offset:41792
	v_cvt_f16_f32_e32 v52, v52
	v_cvt_f16_f32_e32 v53, v53
	v_cvt_f16_f32_e32 v54, v54
	v_cvt_f16_f32_e32 v55, v55
	ds_write_b16 v240, v52 offset:41056
	ds_write_b16 v240, v53 offset:41312
	ds_write_b16 v240, v54 offset:41568
	ds_write_b16 v240, v55 offset:41824
	v_cvt_f16_f32_e32 v44, v44
	v_cvt_f16_f32_e32 v45, v45
	v_cvt_f16_f32_e32 v46, v46
	v_cvt_f16_f32_e32 v47, v47
	ds_write_b16 v240, v44 offset:45056
	ds_write_b16 v240, v45 offset:45312
	ds_write_b16 v240, v46 offset:45568
	ds_write_b16 v240, v47 offset:45824
	v_cvt_f16_f32_e32 v36, v36
	v_cvt_f16_f32_e32 v37, v37
	v_cvt_f16_f32_e32 v38, v38
	v_cvt_f16_f32_e32 v39, v39
	ds_write_b16 v240, v36 offset:45088
	ds_write_b16 v240, v37 offset:45344
	ds_write_b16 v240, v38 offset:45600
	ds_write_b16 v240, v39 offset:45856
	v_cvt_f16_f32_e32 v28, v28
	v_cvt_f16_f32_e32 v29, v29
	v_cvt_f16_f32_e32 v30, v30
	v_cvt_f16_f32_e32 v31, v31
	ds_write_b16 v240, v28 offset:45120
	ds_write_b16 v240, v29 offset:45376
	ds_write_b16 v240, v30 offset:45632
	ds_write_b16 v240, v31 offset:45888
	v_cvt_f16_f32_e32 v20, v20
	v_cvt_f16_f32_e32 v21, v21
	v_cvt_f16_f32_e32 v22, v22
	v_cvt_f16_f32_e32 v23, v23
	ds_write_b16 v240, v20 offset:45152
	ds_write_b16 v240, v21 offset:45408
	ds_write_b16 v240, v22 offset:45664
	ds_write_b16 v240, v23 offset:45920
	s_mulk_i32 s13, 0x4280
	v_or_b32_e32 v0, s20, v128
	v_ashrrev_i32_e32 v1, 31, v0
	v_lshl_add_u64 v[2:3], v[0:1], 1, s[50:51]
	v_subrev_u32_e32 v0, s13, v165
	s_mov_b32 s13, 0
	v_mov_b32_e32 v4, v0
	s_waitcnt lgkmcnt(0)
	s_barrier
